# SSD staging ladder: when the next chunk's flag load is in flight wait vmcnt(1) instead of vmcnt(0) (scalar branch); conv_ffn phantom waits removed; y_inter reverted to compiler order
# baseline (speedup 1.0000x reference)
.LBB0_1012:
	s_and_b32 s35, s47, 1
	s_lshl_b32 s24, s35, 10
	s_add_i32 s54, s24, 0
	s_add_i32 s54, s54, 0x22800
	v_lshlrev_b32_e32 v56, 2, v136
	s_waitcnt lgkmcnt(0)
	s_barrier
	s_waitcnt vmcnt(9)
	ds_write_b128 v152, v[0:3]
	s_waitcnt vmcnt(8)
	ds_write_b128 v152, v[4:7] offset:34816
	s_waitcnt vmcnt(7)
	ds_write_b128 v153, v[8:11]
	s_waitcnt vmcnt(6)
	ds_write_b128 v153, v[12:15] offset:34816
	s_waitcnt vmcnt(5)
	ds_write_b128 v154, v[16:19]
	s_waitcnt vmcnt(4)
	ds_write_b128 v154, v[20:23] offset:34816
	s_waitcnt vmcnt(3)
	ds_write_b128 v155, v[24:27]
	s_waitcnt vmcnt(2)
	ds_write_b128 v155, v[28:31] offset:34816
	s_and_b64 vcc, exec, s[90:91]
	s_cbranch_vccz .Lmy_ssd_flagld_a
	s_waitcnt vmcnt(0)
	s_branch .Lmy_ssd_ladend_a

.Lmy_ssd_ladend_a:
	ds_write2_b64 v156, v[36:37], v[38:39] offset1:4
	ds_write2_b64 v156, v[32:33], v[34:35] offset0:8 offset1:12
	v_mov_b32_e32 v57, s54
	v_add_u32_e32 v58, s54, v56
	ds_read_b32 v57, v57
	ds_read_b32 v58, v58
	s_lshl_b32 s27, s35, 9
	s_add_i32 s34, s27, 0
	s_add_i32 s34, s34, 0x23000
	v_add_u32_e32 v56, s34, v56
	s_waitcnt lgkmcnt(0)
	v_sub_f32_e32 v57, v57, v58
	ds_read_b32 v56, v56
	v_mul_f32_e32 v57, 0x3fb8aa3b, v57
	v_exp_f32_e32 v57, v57
	v_lshlrev_b32_e32 v58, 16, v36
	v_and_b32_e32 v59, 0xffff0000, v36
	v_lshlrev_b32_e32 v60, 16, v37
	s_waitcnt lgkmcnt(0)
	v_mul_f32_e32 v56, v56, v57
	v_and_b32_e32 v61, 0xffff0000, v37
	v_pk_mul_f32 v[58:59], v[56:57], v[58:59] op_sel_hi:[0,1]
	v_pk_mul_f32 v[60:61], v[56:57], v[60:61] op_sel_hi:[0,1]
	v_cvt_pk_bf16_f32 v58, v58, v59
	v_cvt_pk_bf16_f32 v59, v60, v61
	v_lshlrev_b32_e32 v60, 16, v38
	v_and_b32_e32 v61, 0xffff0000, v38
	v_lshlrev_b32_e32 v62, 16, v39
	v_and_b32_e32 v63, 0xffff0000, v39
	v_pk_mul_f32 v[60:61], v[56:57], v[60:61] op_sel_hi:[0,1]
	v_pk_mul_f32 v[62:63], v[56:57], v[62:63] op_sel_hi:[0,1]
	v_cvt_pk_bf16_f32 v60, v60, v61
	v_cvt_pk_bf16_f32 v61, v62, v63
	ds_write2_b64 v157, v[58:59], v[60:61] offset1:4
	v_lshlrev_b32_e32 v58, 16, v32
	v_and_b32_e32 v59, 0xffff0000, v32
	v_lshlrev_b32_e32 v60, 16, v33
	v_and_b32_e32 v61, 0xffff0000, v33
	v_pk_mul_f32 v[58:59], v[56:57], v[58:59] op_sel_hi:[0,1]
	v_pk_mul_f32 v[60:61], v[56:57], v[60:61] op_sel_hi:[0,1]
	v_cvt_pk_bf16_f32 v58, v58, v59
	v_cvt_pk_bf16_f32 v59, v60, v61
	v_lshlrev_b32_e32 v60, 16, v34
	v_and_b32_e32 v61, 0xffff0000, v34
	v_lshlrev_b32_e32 v62, 16, v35
	v_and_b32_e32 v63, 0xffff0000, v35
	s_cmp_lg_u32 s47, 33
	v_pk_mul_f32 v[60:61], v[56:57], v[60:61] op_sel_hi:[0,1]
	v_pk_mul_f32 v[56:57], v[56:57], v[62:63] op_sel_hi:[0,1]
	s_cselect_b64 s[62:63], -1, 0
	v_cvt_pk_bf16_f32 v60, v60, v61
	v_cvt_pk_bf16_f32 v61, v56, v57
	s_and_b64 s[38:39], s[2:3], s[62:63]
	ds_write2_b64 v157, v[58:59], v[60:61] offset0:8 offset1:12
	s_and_saveexec_b64 s[24:25], s[38:39]
	s_xor_b32 s27, s27, 0x200
	v_add_u32_e32 v56, s27, v144
	ds_write_b32 v56, v142
	s_or_b64 exec, exec, s[24:25]
	s_cmp_lt_i32 s26, 0
	s_cbranch_scc1 .LBB0_1018
	s_waitcnt vmcnt(0)
	s_and_saveexec_b64 s[24:25], s[4:5]
	s_cbranch_execz .LBB0_1017
	s_lshl_b32 s66, s26, 3
	s_lshl_b64 s[26:27], s[66:67], 2
	s_add_u32 s26, s31, s26
	s_addc_u32 s27, s43, s27
	v_mov_b32_e32 v56, 1
	global_store_dword v65, v56, s[26:27] sc1

.LBB0_1134:
	s_and_b32 s83, s34, 1
	s_lshl_b32 s20, s83, 10
	s_add_i32 s35, s20, 0
	s_add_i32 s35, s35, 0x22800
	v_lshlrev_b32_e32 v56, 2, v138
	s_waitcnt lgkmcnt(0)
	s_barrier
	s_waitcnt vmcnt(9)
	ds_write_b128 v155, v[0:3]
	s_waitcnt vmcnt(8)
	ds_write_b128 v155, v[4:7] offset:34816
	s_waitcnt vmcnt(7)
	ds_write_b128 v156, v[8:11]
	s_waitcnt vmcnt(6)
	ds_write_b128 v156, v[12:15] offset:34816
	s_waitcnt vmcnt(5)
	ds_write_b128 v157, v[16:19]
	s_waitcnt vmcnt(4)
	ds_write_b128 v157, v[20:23] offset:34816
	s_waitcnt vmcnt(3)
	ds_write_b128 v158, v[24:27]
	s_waitcnt vmcnt(2)
	ds_write_b128 v158, v[28:31] offset:34816
	s_and_b64 vcc, exec, s[90:91]
	s_cbranch_vccz .Lmy_ssd_flagld_b
	s_waitcnt vmcnt(0)
	s_branch .Lmy_ssd_ladend_b

.Lmy_ssd_ladend_b:
	ds_write2_b64 v159, v[36:37], v[38:39] offset1:4
	ds_write2_b64 v159, v[32:33], v[34:35] offset0:8 offset1:12
	v_mov_b32_e32 v57, s35
	v_add_u32_e32 v58, s35, v56
	ds_read_b32 v57, v57 offset:508
	ds_read_b32 v58, v58
	s_lshl_b32 s26, s83, 9
	s_add_i32 s77, s26, 0
	s_add_i32 s77, s77, 0x23000
	v_add_u32_e32 v56, s77, v56
	s_waitcnt lgkmcnt(0)
	v_sub_f32_e32 v57, v57, v58
	ds_read_b32 v56, v56
	v_mul_f32_e32 v57, 0x3fb8aa3b, v57
	v_exp_f32_e32 v57, v57
	v_lshlrev_b32_e32 v58, 16, v36
	v_and_b32_e32 v59, 0xffff0000, v36
	v_lshlrev_b32_e32 v60, 16, v37
	s_waitcnt lgkmcnt(0)
	v_mul_f32_e32 v56, v56, v57
	v_and_b32_e32 v61, 0xffff0000, v37
	v_pk_mul_f32 v[58:59], v[56:57], v[58:59] op_sel_hi:[0,1]
	v_pk_mul_f32 v[60:61], v[56:57], v[60:61] op_sel_hi:[0,1]
	v_cvt_pk_bf16_f32 v58, v58, v59
	v_cvt_pk_bf16_f32 v59, v60, v61
	v_lshlrev_b32_e32 v60, 16, v38
	v_and_b32_e32 v61, 0xffff0000, v38
	v_lshlrev_b32_e32 v62, 16, v39
	v_and_b32_e32 v63, 0xffff0000, v39
	v_pk_mul_f32 v[60:61], v[56:57], v[60:61] op_sel_hi:[0,1]
	v_pk_mul_f32 v[62:63], v[56:57], v[62:63] op_sel_hi:[0,1]
	v_cvt_pk_bf16_f32 v60, v60, v61
	v_cvt_pk_bf16_f32 v61, v62, v63
	ds_write2_b64 v160, v[58:59], v[60:61] offset1:4
	v_lshlrev_b32_e32 v58, 16, v32
	v_and_b32_e32 v59, 0xffff0000, v32
	v_lshlrev_b32_e32 v60, 16, v33
	v_and_b32_e32 v61, 0xffff0000, v33
	v_pk_mul_f32 v[58:59], v[56:57], v[58:59] op_sel_hi:[0,1]
	v_pk_mul_f32 v[60:61], v[56:57], v[60:61] op_sel_hi:[0,1]
	v_cvt_pk_bf16_f32 v58, v58, v59
	v_cvt_pk_bf16_f32 v59, v60, v61
	v_lshlrev_b32_e32 v60, 16, v34
	v_and_b32_e32 v61, 0xffff0000, v34
	v_lshlrev_b32_e32 v62, 16, v35
	v_and_b32_e32 v63, 0xffff0000, v35
	s_cmp_lg_u32 s34, 33
	v_pk_mul_f32 v[60:61], v[56:57], v[60:61] op_sel_hi:[0,1]
	v_pk_mul_f32 v[56:57], v[56:57], v[62:63] op_sel_hi:[0,1]
	s_cselect_b64 s[20:21], -1, 0
	v_cvt_pk_bf16_f32 v60, v60, v61
	v_cvt_pk_bf16_f32 v61, v56, v57
	s_and_b64 s[38:39], s[2:3], s[20:21]
	ds_write2_b64 v160, v[58:59], v[60:61] offset0:8 offset1:12
	s_and_saveexec_b64 s[24:25], s[38:39]
	s_xor_b32 s26, s26, 0x200
	v_add_u32_e32 v56, s26, v145
	ds_write_b32 v56, v144
	s_or_b64 exec, exec, s[24:25]
	s_cmp_lt_i32 s27, 0
	s_cbranch_scc1 .LBB0_1140
	s_waitcnt vmcnt(0)
	s_and_saveexec_b64 s[24:25], s[4:5]
	s_cbranch_execz .LBB0_1139
	s_lshl_b32 s66, s27, 3
	s_lshl_b64 s[26:27], s[66:67], 2
	s_add_u32 s26, s47, s26
	s_addc_u32 s27, s51, s27
	v_mov_b32_e32 v56, 1
	global_store_dword v65, v56, s[26:27] sc1
